# v77 + retention-out tail state-fragment read batching + chunk-kv B-fragment read batching (all LDS read-batching edits combined)
# speedup vs baseline: 1.0103x; 1.0077x over previous
; #define LAS __attribute__((address_space(3)))
; #define MFMA16(a, b, c) __builtin_amdgcn_mfma_f32_16x16x32_bf16(a, b, c, 0, 0, 0)
; __device__ __forceinline__ void retout_items(LAS unsigned char* lds, const GAS bf16_t* proj, const GAS bf16_t* st, const GAS float* gnw, GAS bf16_t* mix, int q0, int qstride, int nit, int tid, int w, int lane) {
;     ...
; #pragma unroll
;         for (int et = 0; et < 4; ++et)
; #pragma unroll
;             for (int c = 0; c < 2; ++c) { const bf16x8 a = *(const LAS bf16x8*)(STs + (16 * et + fr) * SS + 32 * c + 8 * fq); cr[et] = MFMA16(a, qf[c], cr[et]); }
;         const float qd = __builtin_amdgcn_exp2f(lg2 * (float)(ql + 1));
;         float s1 = 0.f;
; #pragma unroll
;         for (int et = 0; et < 4; ++et) { o[et] = o[et] + cr[et] * qd; s1 += (o[et][0] + o[et][1]) + (o[et][2] + o[et][3]); }
;         s1 += __shfl_xor(s1, 16); s1 += __shfl_xor(s1, 32);
;         const float mean = s1 * (1.0f / 64.0f);
;         float s2 = 0.f;
; #pragma unroll
;         for (int et = 0; et < 4; ++et) { o[et] = o[et] - mean; s2 += (o[et][0] * o[et][0] + o[et][1] * o[et][1]) + (o[et][2] * o[et][2] + o[et][3] * o[et][3]); }
;         s2 += __shfl_xor(s2, 16); s2 += __shfl_xor(s2, 32);
;         const float rs = __builtin_amdgcn_rsqf(s2 * (1.0f / 64.0f) + EPSF);
.LBB0_311:
	ds_read_b128 v[70:73], v193 offset:44032
	ds_read_b128 v[102:105], v193 offset:44096
	ds_read_b128 v[106:109], v192 offset:44096
	ds_read_b128 v[110:113], v192 offset:46400
	ds_read_b128 v[228:231], v192 offset:44032
	ds_read_b128 v[234:237], v192 offset:46336
	ds_read_b128 v[242:245], v195 offset:44032
	ds_read_b128 v[246:249], v195 offset:44096
	v_lshl_add_u32 v114, s18, 7, v134
	s_ashr_i32 s81, s80, 31
	s_lshl_b64 s[8:9], s[80:81], 8
	s_add_i32 s25, s25, 1
	s_add_i32 s24, s24, 32
	s_cmp_eq_u32 s25, 3
	s_mov_b32 s81, 0x12c000
	s_waitcnt lgkmcnt(7)
	v_mfma_f32_16x16x32_bf16 v[70:73], v[70:73], v[42:45], 0
	s_waitcnt lgkmcnt(6)
	v_mfma_f32_16x16x32_bf16 v[70:73], v[102:105], v[46:49], v[70:73]
	s_waitcnt lgkmcnt(3)
	v_mfma_f32_16x16x32_bf16 v[102:105], v[228:231], v[42:45], 0
	v_mfma_f32_16x16x32_bf16 v[102:105], v[106:109], v[46:49], v[102:105]
	s_waitcnt lgkmcnt(2)
	v_mfma_f32_16x16x32_bf16 v[106:109], v[234:237], v[42:45], 0
	v_mfma_f32_16x16x32_bf16 v[106:109], v[110:113], v[46:49], v[106:109]
	s_waitcnt lgkmcnt(1)
	v_mfma_f32_16x16x32_bf16 v[42:45], v[242:245], v[42:45], 0
	s_waitcnt lgkmcnt(0)
	v_mfma_f32_16x16x32_bf16 v[110:113], v[246:249], v[46:49], v[42:45]
	s_nop 4
	v_mul_f32_e32 v42, v87, v135
	v_exp_f32_e32 v44, v42
	s_nop 0
	v_pk_fma_f32 v[48:49], v[44:45], v[72:73], v[64:65] op_sel_hi:[0,1,1]
	v_pk_fma_f32 v[62:63], v[44:45], v[70:71], v[62:63] op_sel_hi:[0,1,1]
	v_pk_mov_b32 v[42:43], v[62:63], v[48:49] op_sel:[1,0]
	v_mov_b32_e32 v46, v62
	v_mov_b32_e32 v47, v49
	v_pk_add_f32 v[42:43], v[42:43], v[46:47]
	v_pk_fma_f32 v[60:61], v[44:45], v[104:105], v[60:61] op_sel_hi:[0,1,1]
	v_add_f32_e32 v42, v42, v43
	v_pk_fma_f32 v[58:59], v[44:45], v[102:103], v[58:59] op_sel_hi:[0,1,1]
	v_add_f32_e32 v64, 0, v42
	v_pk_mov_b32 v[42:43], v[58:59], v[60:61] op_sel:[1,0]
	v_mov_b32_e32 v46, v58
	v_mov_b32_e32 v47, v61
	v_pk_add_f32 v[42:43], v[42:43], v[46:47]
	v_pk_fma_f32 v[46:47], v[44:45], v[108:109], v[56:57] op_sel_hi:[0,1,1]
	v_pk_add_f32 v[70:71], v[42:43], v[42:43] op_sel:[0,1] op_sel_hi:[1,0]
	v_pk_fma_f32 v[54:55], v[44:45], v[106:107], v[54:55] op_sel_hi:[0,1,1]
	v_pk_fma_f32 v[42:43], v[44:45], v[112:113], v[68:69] op_sel_hi:[0,1,1]
	v_pk_fma_f32 v[44:45], v[44:45], v[110:111], v[66:67] op_sel_hi:[0,1,1]
	v_add_f32_e32 v56, v54, v55
	v_add_f32_e32 v72, v46, v47
	v_mov_b32_e32 v65, v44
	v_mov_b32_e32 v71, v45
	v_mov_b32_e32 v57, v42
	v_mov_b32_e32 v73, v43
	v_pk_add_f32 v[64:65], v[64:65], v[70:71]
	v_pk_add_f32 v[56:57], v[56:57], v[72:73]
	s_nop 0
	v_pk_add_f32 v[56:57], v[64:65], v[56:57]
	v_and_b32_e32 v64, 64, v232
	v_add_f32_e32 v56, v56, v57
	v_xor_b32_e32 v57, 16, v232
	v_add_u32_e32 v64, 64, v64
	v_cmp_lt_i32_e32 vcc, v57, v64
	s_nop 1
	v_cndmask_b32_e32 v57, v232, v57, vcc
	v_lshlrev_b32_e32 v72, 2, v57
	ds_bpermute_b32 v57, v72, v56
	s_waitcnt lgkmcnt(0)
	v_add_f32_e32 v56, v56, v57
	v_xor_b32_e32 v57, 32, v232
	v_cmp_lt_i32_e32 vcc, v57, v64
	s_nop 1
	v_cndmask_b32_e32 v57, v232, v57, vcc
	v_lshlrev_b32_e32 v73, 2, v57
	ds_bpermute_b32 v57, v73, v56
	s_waitcnt lgkmcnt(0)
	v_add_f32_e32 v87, v56, v57
	v_fmamk_f32 v63, v87, 0xbc800000, v63
	v_fmac_f32_e32 v62, 0xbc800000, v87
	v_fmamk_f32 v49, v87, 0xbc800000, v49
	v_fmac_f32_e32 v48, 0xbc800000, v87
	v_pk_mul_f32 v[56:57], v[48:49], v[48:49]
	v_pk_mul_f32 v[64:65], v[62:63], v[62:63]
	v_fmamk_f32 v59, v87, 0xbc800000, v59
	v_pk_mov_b32 v[66:67], v[64:65], v[56:57] op_sel:[1,0]
	v_mov_b32_e32 v65, v57
	v_pk_add_f32 v[56:57], v[66:67], v[64:65]
	v_fmac_f32_e32 v58, 0xbc800000, v87
	v_fmamk_f32 v61, v87, 0xbc800000, v61
	v_fmac_f32_e32 v60, 0xbc800000, v87
	v_pk_add_f32 v[64:65], v[56:57], v[56:57] op_sel_hi:[0,1]
	v_pk_mul_f32 v[56:57], v[60:61], v[60:61]
	v_pk_mul_f32 v[66:67], v[58:59], v[58:59]
	v_fmac_f32_e32 v54, 0xbc800000, v87
	v_pk_mov_b32 v[68:69], v[66:67], v[56:57] op_sel:[1,0]
	v_mov_b32_e32 v67, v57
	v_pk_add_f32 v[56:57], v[68:69], v[66:67]
	v_fmamk_f32 v55, v87, 0xbc800000, v55
	v_pk_add_f32 v[66:67], v[56:57], v[56:57] op_sel_hi:[0,1]
	v_fmac_f32_e32 v46, 0xbc800000, v87
	v_mul_f32_e32 v56, v54, v54
	v_fmamk_f32 v47, v87, 0xbc800000, v47
	v_pk_fma_f32 v[68:69], v[54:55], v[54:55], v[56:57] op_sel_hi:[1,1,0]
	v_mul_f32_e32 v56, v46, v46
	v_pk_fma_f32 v[70:71], v[46:47], v[46:47], v[56:57] op_sel_hi:[1,1,0]
	v_fmamk_f32 v43, v87, 0xbc800000, v43
	v_fmac_f32_e32 v42, 0xbc800000, v87
	v_fmamk_f32 v56, v87, 0xbc800000, v45
	v_fmac_f32_e32 v44, 0xbc800000, v87
	v_mul_f32_e32 v68, v44, v44
	v_mul_f32_e32 v70, v56, v56
	v_mul_f32_e32 v64, v42, v42
	v_mul_f32_e32 v66, v43, v43
	v_pk_add_f32 v[68:69], v[68:69], v[70:71]
	v_pk_add_f32 v[64:65], v[64:65], v[66:67]
	v_lshlrev_b32_e32 v66, 16, v100
	v_pk_add_f32 v[64:65], v[68:69], v[64:65]
	s_waitcnt vmcnt(3)
	v_mov_b32_e32 v69, v50
	v_add_f32_e32 v45, v64, v65
	ds_bpermute_b32 v57, v72, v45
	v_ashrrev_i32_e32 v64, 8, v114
	v_ashrrev_i32_e32 v65, 31, v64
	v_lshlrev_b64 v[64:65], 12, v[64:65]
	v_lshl_add_u64 v[64:65], v[64:65], 0, s[8:9]
	s_waitcnt lgkmcnt(0)
	v_add_f32_e32 v45, v45, v57
	ds_bpermute_b32 v57, v73, v45
	s_movk_i32 s8, 0xff
	v_and_or_b32 v64, v114, s8, v64
	v_lshlrev_b64 v[64:65], 7, v[64:65]
	s_waitcnt lgkmcnt(0)
; __device__ __forceinline__ unsigned cvt_pk_bf16(float lo, float hi) { unsigned r; asm volatile("v_cvt_pk_bf16_f32 %0, %1, %2" : "=v"(r) : "v"(lo), "v"(hi)); return r; }
; #define GAS __attribute__((address_space(1)))
; __device__ __forceinline__ size_t TX(int row, int col) { return ((((size_t)(row >> 8) * 16 + (col >> 6)) * 256 + (row & 255)) << 6) + (col & 63); }
; __device__ __forceinline__ float bf2f(unsigned b) { return __uint_as_float(b << 16); }
; __device__ __forceinline__ float silu_f(float v) { return v * __builtin_amdgcn_rcpf(1.f + __expf(-v)); }
; __device__ __forceinline__ void retout_items(LAS unsigned char* lds, const GAS bf16_t* proj, const GAS bf16_t* st, const GAS float* gnw, GAS bf16_t* mix, int q0, int qstride, int nit, int tid, int w, int lane) {
;     ...
;         const float rs = __builtin_amdgcn_rsqf(s2 * (1.0f / 64.0f) + EPSF);
; #pragma unroll
;         for (int et = 0; et < 4; ++et) {
;             const int col = 64 * h + 16 * et + 4 * fq;
;             const u32x2 gv = gvv[et]; const f32x4 gn = gnv[et];
;             f32x4 y;
;             y[0] = o[et][0] * rs * gn[0] * silu_f(bf2f(gv.x & 0xffffu)); y[1] = o[et][1] * rs * gn[1] * silu_f(bf2f(gv.x >> 16));
;             y[2] = o[et][2] * rs * gn[2] * silu_f(bf2f(gv.y & 0xffffu)); y[3] = o[et][3] * rs * gn[3] * silu_f(bf2f(gv.y >> 16));
;             u32x2 wv; wv.x = cvt_pk_bf16(y[0], y[1]); wv.y = cvt_pk_bf16(y[2], y[3]);
;             *(GAS u32x2*)(mix + TX(tq, col)) = wv;
;         }
;         __syncthreads();
	v_add_f32_e32 v45, v45, v57
	v_fmamk_f32 v45, v45, 0x3c800000, v233
	v_rsq_f32_e32 v45, v45
	v_mul_f32_e32 v57, 0xbfb8aa3b, v66
	v_exp_f32_e32 v57, v57
	v_mul_f32_e32 v67, v62, v45
	v_and_b32_e32 v62, 0xffff0000, v100
	v_mul_f32_e32 v50, 0xbfb8aa3b, v62
	v_exp_f32_e32 v50, v50
	v_add_f32_e32 v57, 1.0, v57
	v_rcp_f32_e32 v68, v57
	v_mul_f32_e32 v63, v63, v45
	v_add_f32_e32 v50, 1.0, v50
	v_rcp_f32_e32 v50, v50
	v_pk_mul_f32 v[66:67], v[68:69], v[66:67]
	v_mul_f32_e32 v49, v49, v45
	v_mul_f32_e32 v57, v66, v67
	v_pk_mul_f32 v[50:51], v[50:51], v[62:63]
	v_mov_b32_e32 v63, v52
	v_mul_f32_e32 v66, v50, v51
	v_lshlrev_b32_e32 v50, 16, v101
	v_mul_f32_e32 v51, v48, v45
	v_mul_f32_e32 v48, 0xbfb8aa3b, v50
	v_exp_f32_e32 v48, v48
	s_nop 0
	v_add_f32_e32 v48, 1.0, v48
	v_rcp_f32_e32 v62, v48
	v_and_b32_e32 v48, 0xffff0000, v101
	v_mov_b64_e32 v[100:101], v[90:91]
	v_pk_mul_f32 v[50:51], v[62:63], v[50:51]
	s_nop 0
	v_mul_f32_e32 v51, v50, v51
	v_mul_f32_e32 v50, 0xbfb8aa3b, v48
	v_exp_f32_e32 v50, v50
	s_nop 0
	v_add_f32_e32 v50, 1.0, v50
	v_rcp_f32_e32 v52, v50
	v_cvt_pk_bf16_f32 v50, v57, v66
	s_nop 0
	v_pk_mul_f32 v[48:49], v[52:53], v[48:49]
	s_nop 0
	v_mul_f32_e32 v48, v48, v49
	v_cvt_pk_bf16_f32 v51, v51, v48
	v_lshl_add_u64 v[48:49], v[84:85], 0, v[64:65]
	global_store_dwordx2 v[48:49], v[50:51], off
	v_lshlrev_b32_e32 v50, 16, v98
	v_mul_f32_e32 v52, 0xbfb8aa3b, v50
	v_exp_f32_e32 v52, v52
	v_mul_f32_e32 v51, v58, v45
	s_waitcnt vmcnt(3)
	v_mov_b32_e32 v53, v38
	v_add_f32_e32 v52, 1.0, v52
	v_rcp_f32_e32 v52, v52
	s_nop 0
	v_pk_mul_f32 v[50:51], v[52:53], v[50:51]
	s_nop 0
	v_mul_f32_e32 v52, v50, v51
	v_and_b32_e32 v50, 0xffff0000, v98
	v_mul_f32_e32 v38, 0xbfb8aa3b, v50
	v_exp_f32_e32 v38, v38
	v_mul_f32_e32 v51, v59, v45
	v_add_f32_e32 v38, 1.0, v38
	v_rcp_f32_e32 v38, v38
	s_nop 0
	v_pk_mul_f32 v[38:39], v[38:39], v[50:51]
	s_nop 0
	v_mul_f32_e32 v53, v38, v39
	v_lshlrev_b32_e32 v38, 16, v99
	v_mul_f32_e32 v50, 0xbfb8aa3b, v38
	v_exp_f32_e32 v50, v50
	v_mul_f32_e32 v39, v60, v45
	v_mov_b32_e32 v51, v40
	v_add_f32_e32 v50, 1.0, v50
	v_rcp_f32_e32 v50, v50
	s_nop 0
	v_pk_mul_f32 v[38:39], v[50:51], v[38:39]
	s_nop 0
	v_mul_f32_e32 v50, v38, v39
	v_and_b32_e32 v38, 0xffff0000, v99
	v_mul_f32_e32 v40, 0xbfb8aa3b, v38
	v_exp_f32_e32 v40, v40
	v_mul_f32_e32 v39, v61, v45
	v_mov_b64_e32 v[98:99], v[92:93]
	v_add_f32_e32 v40, 1.0, v40
	v_rcp_f32_e32 v40, v40
	s_nop 0
	v_pk_mul_f32 v[38:39], v[40:41], v[38:39]
	s_nop 0
	v_mul_f32_e32 v39, v38, v39
	v_cvt_pk_bf16_f32 v38, v52, v53
	v_cvt_pk_bf16_f32 v39, v50, v39
	global_store_dwordx2 v[48:49], v[38:39], off offset:32
	v_lshlrev_b32_e32 v38, 16, v88
	v_mul_f32_e32 v40, 0xbfb8aa3b, v38
	v_exp_f32_e32 v40, v40
	v_mul_f32_e32 v39, v54, v45
	s_waitcnt vmcnt(3)
	v_mov_b32_e32 v41, v34
	v_add_f32_e32 v40, 1.0, v40
	v_rcp_f32_e32 v40, v40
	s_nop 0
	v_pk_mul_f32 v[38:39], v[40:41], v[38:39]
	s_nop 0
	v_mul_f32_e32 v40, v38, v39
	v_and_b32_e32 v38, 0xffff0000, v88
	v_mul_f32_e32 v34, 0xbfb8aa3b, v38
	v_exp_f32_e32 v34, v34
	v_mul_f32_e32 v39, v55, v45
	v_add_f32_e32 v34, 1.0, v34
	v_rcp_f32_e32 v34, v34
	s_nop 0
	v_pk_mul_f32 v[34:35], v[34:35], v[38:39]
	s_nop 0
	v_mul_f32_e32 v41, v34, v35
	v_lshlrev_b32_e32 v34, 16, v89
	v_mul_f32_e32 v38, 0xbfb8aa3b, v34
	v_exp_f32_e32 v38, v38
	v_mul_f32_e32 v35, v46, v45
	v_mov_b32_e32 v39, v36
	v_add_f32_e32 v38, 1.0, v38
	v_rcp_f32_e32 v38, v38
	s_nop 0
	v_pk_mul_f32 v[34:35], v[38:39], v[34:35]
	s_nop 0
	v_mul_f32_e32 v38, v34, v35
	v_and_b32_e32 v34, 0xffff0000, v89
	v_mul_f32_e32 v36, 0xbfb8aa3b, v34
	v_exp_f32_e32 v36, v36
	v_mul_f32_e32 v35, v47, v45
	v_mov_b64_e32 v[88:89], v[94:95]
	v_add_f32_e32 v36, 1.0, v36
	v_rcp_f32_e32 v36, v36
	s_nop 0
	v_pk_mul_f32 v[34:35], v[36:37], v[34:35]
	s_nop 0
	v_mul_f32_e32 v35, v34, v35
	v_cvt_pk_bf16_f32 v34, v40, v41
	v_cvt_pk_bf16_f32 v35, v38, v35
	global_store_dwordx2 v[48:49], v[34:35], off offset:64
	v_lshlrev_b32_e32 v34, 16, v82
	v_mul_f32_e32 v36, 0xbfb8aa3b, v34
	v_exp_f32_e32 v36, v36
	v_mul_f32_e32 v35, v44, v45
	s_waitcnt vmcnt(3)
	v_mov_b32_e32 v37, v30
	v_add_f32_e32 v36, 1.0, v36
	v_rcp_f32_e32 v36, v36
	s_nop 0
	v_pk_mul_f32 v[34:35], v[36:37], v[34:35]
	s_nop 0
	v_mul_f32_e32 v36, v34, v35
	v_and_b32_e32 v34, 0xffff0000, v82
	v_mul_f32_e32 v30, 0xbfb8aa3b, v34
	v_exp_f32_e32 v30, v30
	v_mul_f32_e32 v35, v56, v45
	v_add_f32_e32 v30, 1.0, v30
	v_rcp_f32_e32 v30, v30
	s_nop 0
	v_pk_mul_f32 v[30:31], v[30:31], v[34:35]
	s_nop 0
	v_mul_f32_e32 v37, v30, v31
	v_lshlrev_b32_e32 v30, 16, v83
	v_mul_f32_e32 v34, 0xbfb8aa3b, v30
	v_exp_f32_e32 v34, v34
	v_mul_f32_e32 v31, v42, v45
	v_mov_b32_e32 v35, v32
	v_add_f32_e32 v34, 1.0, v34
	v_rcp_f32_e32 v34, v34
	s_nop 0
	v_pk_mul_f32 v[30:31], v[34:35], v[30:31]
	s_nop 0
	v_mul_f32_e32 v34, v30, v31
	v_and_b32_e32 v30, 0xffff0000, v83
	v_mul_f32_e32 v32, 0xbfb8aa3b, v30
	v_exp_f32_e32 v32, v32
	v_mul_f32_e32 v31, v43, v45
	v_mov_b64_e32 v[44:45], v[24:25]
	v_mov_b64_e32 v[82:83], v[96:97]
	v_add_f32_e32 v32, 1.0, v32
	v_rcp_f32_e32 v32, v32
	v_mov_b64_e32 v[42:43], v[22:23]
	v_pk_mul_f32 v[30:31], v[32:33], v[30:31]
	s_nop 0
	v_mul_f32_e32 v31, v30, v31
	v_cvt_pk_bf16_f32 v30, v36, v37
	v_cvt_pk_bf16_f32 v31, v34, v31
	global_store_dwordx2 v[48:49], v[30:31], off offset:96
	v_mov_b64_e32 v[48:49], v[28:29]
	v_mov_b64_e32 v[46:47], v[26:27]
	s_barrier
	s_cbranch_scc1 .LBB0_364
